# P1: per-row rstd for the epilogue loaded at tile start (v248-255) instead of epilogue start
# speedup vs baseline: 1.0062x; 1.0062x over previous
.LBB0_109:
	v_or_b32_e32 v130, s24, v146
	v_add_u32_e32 v136, s25, v130
	v_or_b32_e32 v140, 16, v136
	v_ashrrev_i32_e32 v137, 31, v136
	v_ashrrev_i32_e32 v141, 31, v140
	v_lshl_add_u64 v[138:139], v[136:137], 2, s[2:3]
	v_lshl_add_u64 v[132:133], v[140:141], 2, s[2:3]
	v_or_b32_e32 v134, s22, v145
	v_or_b32_e32 v134, s23, v134
	v_mov_b64_e32 v[132:133], s[60:61]
	v_ashrrev_i32_e32 v135, 31, v134
	v_mad_i64_i32 v[142:143], s[22:23], v136, s36, v[132:133]
	v_lshlrev_b64 v[134:135], 1, v[134:135]
	v_mad_i64_i32 v[140:141], s[22:23], v140, s36, v[132:133]
	v_lshl_add_u64 v[142:143], v[142:143], 0, v[134:135]
	v_lshl_add_u64 v[140:141], v[140:141], 0, v[134:135]
	s_add_i32 s37, s37, s58
	s_cmpk_gt_i32 s37, 0x4a3
	s_cbranch_scc1 .Lp1pf_last
	s_mov_b32 s96, 1
	s_and_b32 s27, s37, 7
	s_lshr_b32 s26, s37, 3
	s_mul_i32 s28, s27, 0x95
	s_mul_i32 s29, s27, 0x94
	s_add_i32 s29, s29, 4
	s_cmp_gt_u32 s27, 3
	s_cselect_b32 s28, s29, s28
	s_add_i32 s26, s28, s26
	s_mul_hi_u32 s27, s26, 0x38e38e39
	s_lshr_b32 s27, s27, 5
	s_mul_i32 s28, s27, 0x90
	s_sub_i32 s26, s26, s28
	s_cmp_lt_u32 s27, 8
	s_cselect_b32 s28, 3, 1
	s_cselect_b32 s29, 7, 1
	s_lshr_b32 s30, s26, s28
	s_and_b32 s26, s26, s29
	s_lshl_b32 s27, s27, 3
	s_add_i32 s26, s26, s27
	s_lshl_b32 s26, s26, 19
	s_lshl_b32 s28, s30, 19
	s_add_u32 s26, s34, s26
	s_addc_u32 s27, s35, 0
	s_add_u32 s28, s76, s28
	s_addc_u32 s29, s77, 0
	s_add_u32 s42, s28, 0x40000
	s_addc_u32 s43, s29, 0
	s_add_u32 s50, s26, 0x40000
	s_addc_u32 s51, s27, 0
	s_add_i32 m0, s40, 0x10000
	s_nop 0
	global_load_lds_dwordx4 v243, s[28:29]
	s_add_i32 m0, s40, 0x12000
	s_nop 0
	global_load_lds_dwordx4 v244, s[28:29]
	s_add_i32 m0, s40, 0
	s_nop 0
	global_load_lds_dwordx4 v245, s[26:27]
	s_add_i32 m0, s40, 0x2000
	s_nop 0
	global_load_lds_dwordx4 v246, s[26:27]
	s_add_i32 m0, s40, 0x14000
	s_nop 0
	global_load_lds_dwordx4 v243, s[42:43]
	s_add_i32 m0, s40, 0x16000
	s_nop 0
	global_load_lds_dwordx4 v244, s[42:43]
	s_add_i32 m0, s40, 0x4000
	s_nop 0
	global_load_lds_dwordx4 v245, s[50:51]
	s_add_i32 m0, s40, 0x6000
	s_nop 0
	global_load_lds_dwordx4 v246, s[50:51]
	s_branch .Lp1pf_done

.Lp1pf_dummy:
.Lp1pf_done:
	s_cmpk_gt_i32 s37, 0x4a3
	v_mul_f32_e32 v120, v120, v248
	v_mul_f32_e32 v121, v121, v248
	v_mul_f32_e32 v117, v117, v248
	v_mul_f32_e32 v122, v122, v248
	v_mul_f32_e32 v123, v123, v248
	v_mul_f32_e32 v124, v124, v248
	v_mul_f32_e32 v101, v101, v249
	v_mul_f32_e32 v118, v118, v248
	v_mul_f32_e32 v119, v119, v248
	v_mul_f32_e32 v145, v114, v248
	v_mul_f32_e32 v146, v115, v248
	v_mul_f32_e32 v147, v116, v248
	v_mul_f32_e32 v125, v125, v248
	v_cvt_pk_bf16_f32 v114, v118, v119
	v_cvt_pk_bf16_f32 v115, v120, v121
	v_cvt_pk_bf16_f32 v116, v145, v146
	v_cvt_pk_bf16_f32 v117, v147, v117
	v_cvt_pk_bf16_f32 v120, v122, v123
	v_cvt_pk_bf16_f32 v121, v124, v125
	v_mul_f32_e32 v102, v102, v249
	v_mul_f32_e32 v103, v103, v249
	v_mul_f32_e32 v104, v104, v249
	v_mul_f32_e32 v105, v105, v249
	v_mul_f32_e32 v122, v98, v249
	v_mul_f32_e32 v123, v99, v249
	v_mul_f32_e32 v124, v100, v249
	v_cvt_pk_bf16_f32 v98, v102, v103
	v_cvt_pk_bf16_f32 v99, v104, v105
	v_cvt_pk_bf16_f32 v100, v122, v123
	v_cvt_pk_bf16_f32 v101, v124, v101
	v_mul_f32_e32 v126, v126, v248
	v_mul_f32_e32 v127, v127, v248
	v_mul_f32_e32 v128, v128, v248
	v_mul_f32_e32 v129, v129, v248
	v_cvt_pk_bf16_f32 v118, v126, v127
	v_cvt_pk_bf16_f32 v119, v128, v129
	v_mul_f32_e32 v110, v110, v249
	v_mul_f32_e32 v111, v111, v249
	v_mul_f32_e32 v112, v112, v249
	v_mul_f32_e32 v113, v113, v249
	v_mul_f32_e32 v106, v106, v249
	v_mul_f32_e32 v107, v107, v249
	v_mul_f32_e32 v108, v108, v249
	v_mul_f32_e32 v109, v109, v249
	global_store_dwordx4 v[142:143], v[114:117], off
	global_store_dwordx4 v[142:143], v[118:121], off offset:256
	v_cvt_pk_bf16_f32 v102, v110, v111
	v_cvt_pk_bf16_f32 v103, v112, v113
	v_cvt_pk_bf16_f32 v104, v106, v107
	v_cvt_pk_bf16_f32 v105, v108, v109
	global_store_dwordx4 v[140:141], v[98:101], off
	global_store_dwordx4 v[140:141], v[102:105], off offset:256
	v_or_b32_e32 v98, 48, v136
	v_ashrrev_i32_e32 v99, 31, v98
	v_lshl_add_u64 v[100:101], v[98:99], 2, s[2:3]
	v_or_b32_e32 v99, 32, v136
	v_add_u32_e32 v100, 0x80, v136
	v_mad_i64_i32 v[102:103], s[22:23], v99, s36, v[132:133]
	v_mad_i64_i32 v[98:99], s[22:23], v98, s36, v[132:133]
	v_ashrrev_i32_e32 v101, 31, v100
	v_lshl_add_u64 v[102:103], v[102:103], 0, v[134:135]
	v_lshl_add_u64 v[98:99], v[98:99], 0, v[134:135]
	v_lshl_add_u64 v[104:105], v[100:101], 2, s[2:3]
	v_mul_f32_e32 v78, v78, v250
	v_mul_f32_e32 v79, v79, v250
	v_mul_f32_e32 v80, v80, v250
	v_mul_f32_e32 v81, v81, v250
	v_mul_f32_e32 v74, v74, v250
	v_mul_f32_e32 v75, v75, v250
	v_mul_f32_e32 v76, v76, v250
	v_mul_f32_e32 v77, v77, v250
	v_mul_f32_e32 v110, v66, v251
	v_mul_f32_e32 v111, v67, v251
	v_mul_f32_e32 v112, v68, v251
	v_mul_f32_e32 v113, v69, v251
	v_cvt_pk_bf16_f32 v66, v78, v79
	v_cvt_pk_bf16_f32 v67, v80, v81
	v_cvt_pk_bf16_f32 v68, v74, v75
	v_cvt_pk_bf16_f32 v69, v76, v77
	v_mul_f32_e32 v94, v94, v250
	v_mul_f32_e32 v95, v95, v250
	v_mul_f32_e32 v96, v96, v250
	v_mul_f32_e32 v97, v97, v250
	v_mul_f32_e32 v90, v90, v250
	v_mul_f32_e32 v91, v91, v250
	v_mul_f32_e32 v92, v92, v250
	v_mul_f32_e32 v93, v93, v250
	v_mul_f32_e32 v101, v70, v251
	v_mul_f32_e32 v106, v71, v251
	v_mul_f32_e32 v108, v72, v251
	v_mul_f32_e32 v109, v73, v251
	v_mul_f32_e32 v86, v86, v251
	v_mul_f32_e32 v87, v87, v251
	v_mul_f32_e32 v88, v88, v251
	v_mul_f32_e32 v89, v89, v251
	v_mul_f32_e32 v82, v82, v251
	v_mul_f32_e32 v83, v83, v251
	v_mul_f32_e32 v84, v84, v251
	v_mul_f32_e32 v85, v85, v251
	v_cvt_pk_bf16_f32 v70, v94, v95
	v_cvt_pk_bf16_f32 v71, v96, v97
	v_cvt_pk_bf16_f32 v72, v90, v91
	v_cvt_pk_bf16_f32 v73, v92, v93
	v_cvt_pk_bf16_f32 v74, v101, v106
	v_cvt_pk_bf16_f32 v75, v108, v109
	v_cvt_pk_bf16_f32 v76, v110, v111
	v_cvt_pk_bf16_f32 v77, v112, v113
	v_cvt_pk_bf16_f32 v78, v86, v87
	v_cvt_pk_bf16_f32 v79, v88, v89
	v_cvt_pk_bf16_f32 v80, v82, v83
	v_cvt_pk_bf16_f32 v81, v84, v85
	global_store_dwordx4 v[102:103], v[66:69], off
	global_store_dwordx4 v[102:103], v[70:73], off offset:256
	global_store_dwordx4 v[98:99], v[74:77], off
	global_store_dwordx4 v[98:99], v[78:81], off offset:256
	v_add_u32_e32 v66, 0x90, v136
	v_ashrrev_i32_e32 v67, 31, v66
	v_lshl_add_u64 v[68:69], v[66:67], 2, s[2:3]
	v_add_u32_e32 v68, 0xa0, v136
	v_mad_i64_i32 v[70:71], s[22:23], v100, s36, v[132:133]
	v_mad_i64_i32 v[66:67], s[22:23], v66, s36, v[132:133]
	v_ashrrev_i32_e32 v69, 31, v68
	v_lshl_add_u64 v[70:71], v[70:71], 0, v[134:135]
	v_lshl_add_u64 v[66:67], v[66:67], 0, v[134:135]
	v_lshl_add_u64 v[72:73], v[68:69], 2, s[2:3]
	v_mul_f32_e32 v54, v54, v252
	v_mul_f32_e32 v55, v55, v252
	v_mul_f32_e32 v56, v56, v252
	v_mul_f32_e32 v57, v57, v252
	v_mul_f32_e32 v46, v46, v252
	v_mul_f32_e32 v47, v47, v252
	v_mul_f32_e32 v48, v48, v252
	v_mul_f32_e32 v49, v49, v252
	v_mul_f32_e32 v78, v34, v253
	v_mul_f32_e32 v79, v35, v253
	v_mul_f32_e32 v80, v36, v253
	v_mul_f32_e32 v81, v37, v253
	v_cvt_pk_bf16_f32 v34, v54, v55
	v_cvt_pk_bf16_f32 v35, v56, v57
	v_cvt_pk_bf16_f32 v36, v46, v47
	v_cvt_pk_bf16_f32 v37, v48, v49
	v_mul_f32_e32 v62, v62, v252
	v_mul_f32_e32 v63, v63, v252
	v_mul_f32_e32 v64, v64, v252
	v_mul_f32_e32 v65, v65, v252
	v_mul_f32_e32 v58, v58, v252
	v_mul_f32_e32 v59, v59, v252
	v_mul_f32_e32 v60, v60, v252
	v_mul_f32_e32 v61, v61, v252
	v_mul_f32_e32 v69, v38, v253
	v_mul_f32_e32 v74, v39, v253
	v_mul_f32_e32 v76, v40, v253
	v_mul_f32_e32 v77, v41, v253
	v_mul_f32_e32 v50, v50, v253
	v_mul_f32_e32 v51, v51, v253
	v_mul_f32_e32 v52, v52, v253
	v_mul_f32_e32 v53, v53, v253
	v_mul_f32_e32 v82, v42, v253
	v_mul_f32_e32 v83, v43, v253
	v_mul_f32_e32 v84, v44, v253
	v_mul_f32_e32 v75, v45, v253
	v_cvt_pk_bf16_f32 v38, v62, v63
	v_cvt_pk_bf16_f32 v39, v64, v65
	v_cvt_pk_bf16_f32 v40, v58, v59
	v_cvt_pk_bf16_f32 v41, v60, v61
	v_cvt_pk_bf16_f32 v42, v69, v74
	v_cvt_pk_bf16_f32 v43, v76, v77
	v_cvt_pk_bf16_f32 v44, v78, v79
	v_cvt_pk_bf16_f32 v45, v80, v81
	v_cvt_pk_bf16_f32 v46, v50, v51
	v_cvt_pk_bf16_f32 v47, v52, v53
	v_cvt_pk_bf16_f32 v48, v82, v83
	v_cvt_pk_bf16_f32 v49, v84, v75
	global_store_dwordx4 v[70:71], v[34:37], off
	global_store_dwordx4 v[70:71], v[38:41], off offset:256
	global_store_dwordx4 v[66:67], v[42:45], off
	global_store_dwordx4 v[66:67], v[46:49], off offset:256
	v_add_u32_e32 v34, 0xb0, v136
	v_ashrrev_i32_e32 v35, 31, v34
	v_lshl_add_u64 v[36:37], v[34:35], 2, s[2:3]
	v_mad_i64_i32 v[36:37], s[22:23], v68, s36, v[132:133]
	v_mad_i64_i32 v[34:35], s[22:23], v34, s36, v[132:133]
	v_lshl_add_u64 v[36:37], v[36:37], 0, v[134:135]
	v_lshl_add_u64 v[34:35], v[34:35], 0, v[134:135]
	v_mul_f32_e32 v22, v22, v254
	v_mul_f32_e32 v23, v23, v254
	v_mul_f32_e32 v24, v24, v254
	v_mul_f32_e32 v25, v25, v254
	v_mul_f32_e32 v14, v14, v254
	v_mul_f32_e32 v15, v15, v254
	v_mul_f32_e32 v16, v16, v254
	v_mul_f32_e32 v17, v17, v254
	v_mul_f32_e32 v43, v2, v255
	v_mul_f32_e32 v44, v3, v255
	v_mul_f32_e32 v45, v4, v255
	v_mul_f32_e32 v46, v5, v255
	v_cvt_pk_bf16_f32 v2, v22, v23
	v_cvt_pk_bf16_f32 v3, v24, v25
	v_cvt_pk_bf16_f32 v4, v14, v15
	v_cvt_pk_bf16_f32 v5, v16, v17
	v_mul_f32_e32 v30, v30, v254
	v_mul_f32_e32 v31, v31, v254
	v_mul_f32_e32 v32, v32, v254
	v_mul_f32_e32 v33, v33, v254
	v_mul_f32_e32 v26, v26, v254
	v_mul_f32_e32 v27, v27, v254
	v_mul_f32_e32 v28, v28, v254
	v_mul_f32_e32 v29, v29, v254
	v_mul_f32_e32 v38, v6, v255
	v_mul_f32_e32 v40, v7, v255
	v_mul_f32_e32 v41, v8, v255
	v_mul_f32_e32 v42, v9, v255
	v_mul_f32_e32 v18, v18, v255
	v_mul_f32_e32 v19, v19, v255
	v_mul_f32_e32 v20, v20, v255
	v_mul_f32_e32 v21, v21, v255
	v_mul_f32_e32 v47, v10, v255
	v_mul_f32_e32 v48, v11, v255
	v_mul_f32_e32 v49, v12, v255
	v_mul_f32_e32 v39, v13, v255
	v_cvt_pk_bf16_f32 v6, v30, v31
	v_cvt_pk_bf16_f32 v7, v32, v33
	v_cvt_pk_bf16_f32 v8, v26, v27
	v_cvt_pk_bf16_f32 v9, v28, v29
	v_cvt_pk_bf16_f32 v10, v38, v40
	v_cvt_pk_bf16_f32 v11, v41, v42
	v_cvt_pk_bf16_f32 v12, v43, v44
	v_cvt_pk_bf16_f32 v13, v45, v46
	v_cvt_pk_bf16_f32 v14, v18, v19
	v_cvt_pk_bf16_f32 v15, v20, v21
	v_cvt_pk_bf16_f32 v16, v47, v48
	v_cvt_pk_bf16_f32 v17, v49, v39
	global_store_dwordx4 v[36:37], v[2:5], off
	global_store_dwordx4 v[36:37], v[6:9], off offset:256
	global_store_dwordx4 v[34:35], v[10:13], off
	global_store_dwordx4 v[34:35], v[14:17], off offset:256
	s_barrier
	s_cbranch_scc1 .LBB0_120

.LBB0_116:
	v_lshrrev_b32_e32 v27, 1, v26
	v_and_b32_e32 v145, 24, v27
	s_lshl_b32 s23, s45, 5
	v_and_b32_e32 v146, 15, v26
	v_lshlrev_b32_e32 v27, 1, v145
	v_lshlrev_b32_e32 v26, 2, v26
	s_and_b32 s23, s23, 0x60
	s_lshl_b32 s25, s44, 6
	v_lshl_or_b32 v27, v146, 6, v27
	v_and_b32_e32 v26, 32, v26
	s_lshl_b32 s44, s44, 13
	s_lshl_b32 s45, s23, 7
	s_add_i32 m0, s40, 0x18000
	v_lshl_add_u64 v[10:11], v[10:11], 0, s[4:5]
	v_bitop3_b32 v148, v27, s45, v26 bitop3:0xde
	v_bitop3_b32 v26, v27, s44, v26 bitop3:0xde
	s_barrier
	global_load_lds_dwordx4 v[10:11], off
	v_lshl_add_u64 v[8:9], v[8:9], 0, s[4:5]
	s_add_i32 m0, s40, 0x1a000
	s_add_i32 s44, s40, 0x8000
	s_add_i32 s45, s40, 0xa000
	global_load_lds_dwordx4 v[8:9], off
	v_lshl_add_u64 v[6:7], v[6:7], 0, s[4:5]
	s_mov_b32 m0, s44
	s_add_u32 s28, s28, 0x40080
	global_load_lds_dwordx4 v[6:7], off
	v_lshl_add_u64 v[4:5], v[4:5], 0, s[4:5]
	s_mov_b32 m0, s45
	s_addc_u32 s29, s29, 0
	global_load_lds_dwordx4 v[4:5], off
	s_add_i32 m0, s40, 0x1c000
	v_lshl_add_u64 v[4:5], s[28:29], 0, v[130:131]
	global_load_lds_dwordx4 v[4:5], off
	v_lshl_add_u64 v[2:3], s[28:29], 0, v[2:3]
	s_add_i32 m0, s40, 0x1e000
	s_sub_i32 s29, s46, s49
	global_load_lds_dwordx4 v[2:3], off
	v_lshlrev_b32_e32 v2, 14, v12
	v_and_b32_e32 v2, 0xffff8000, v2
	v_and_b32_e32 v3, 1, v12
	s_sub_i32 s29, s29, s48
	v_lshl_add_u32 v2, v17, 11, v2
	v_lshlrev_b32_e32 v3, 6, v3
	s_sext_i32_i16 s29, s29
	v_or_b32_e32 v2, v2, v3
	v_lshlrev_b32_e32 v4, 1, v18
	s_lshl_b32 s28, s47, 11
	s_lshl_b32 s29, s29, 8
	v_add_u32_e32 v130, v2, v4
	v_lshlrev_b32_e32 v2, 14, v19
	s_add_i32 s28, s28, s29
	v_and_b32_e32 v2, 0xffff8000, v2
	v_and_b32_e32 v5, 1, v19
	s_ashr_i32 s29, s28, 31
	v_lshl_add_u32 v2, v24, 11, v2
	v_lshlrev_b32_e32 v5, 6, v5
	s_lshl_b64 s[28:29], s[28:29], 11
	v_or_b32_e32 v2, v2, v5
	v_lshlrev_b32_e32 v6, 1, v25
	v_lshl_add_u64 v[136:137], s[28:29], 0, v[130:131]
	v_add_u32_e32 v130, v2, v6
	v_add_u32_e32 v2, v13, v14
	v_add3_u32 v2, v2, v15, v16
	v_lshl_or_b32 v2, v2, 11, v3
	v_lshl_add_u64 v[138:139], s[28:29], 0, v[130:131]
	v_add_u32_e32 v130, v2, v4
	v_add_u32_e32 v2, v20, v21
	v_add3_u32 v2, v2, v22, v23
	s_waitcnt vmcnt(6)
	v_lshl_or_b32 v2, v2, 11, v5
	v_lshl_add_u64 v[140:141], s[30:31], 0, v[130:131]
	v_add_u32_e32 v130, v2, v6
	v_or_b32_e32 v126, s24, v146
	v_add_u32_e32 v126, s25, v126
	v_mov_b32_e32 v127, 0
	v_or_b32_e32 v128, 16, v126
	v_mov_b32_e32 v129, 0
	v_lshl_add_u64 v[126:127], v[126:127], 2, s[2:3]
	v_lshl_add_u64 v[128:129], v[128:129], 2, s[2:3]
	global_load_dword v248, v[126:127], off
	global_load_dword v249, v[128:129], off
	global_load_dword v250, v[126:127], off offset:128
	global_load_dword v251, v[126:127], off offset:192
	global_load_dword v252, v[126:127], off offset:512
	global_load_dword v253, v[126:127], off offset:576
	global_load_dword v254, v[126:127], off offset:640
	global_load_dword v255, v[126:127], off offset:704
	v_mov_b32_e32 v2, 0
	s_mov_b32 s46, -2
	v_add_u32_e32 v147, 0, v26
	s_mov_b64 s[28:29], s[76:77]
	v_mov_b32_e32 v3, v2
	v_mov_b32_e32 v4, v2
	v_mov_b32_e32 v5, v2
	v_mov_b32_e32 v6, v2
	v_mov_b32_e32 v7, v2
	v_mov_b32_e32 v8, v2
	v_mov_b32_e32 v9, v2
	v_mov_b32_e32 v10, v2
	v_mov_b32_e32 v11, v2
	v_mov_b32_e32 v12, v2
	v_mov_b32_e32 v13, v2
	v_mov_b32_e32 v14, v2
	v_mov_b32_e32 v15, v2
	v_mov_b32_e32 v16, v2
	v_mov_b32_e32 v17, v2
	v_mov_b32_e32 v18, v2
	v_mov_b32_e32 v19, v2
	v_mov_b32_e32 v20, v2
	v_mov_b32_e32 v21, v2
	v_mov_b32_e32 v22, v2
	v_mov_b32_e32 v23, v2
	v_mov_b32_e32 v24, v2
	v_mov_b32_e32 v25, v2
	v_mov_b32_e32 v26, v2
	v_mov_b32_e32 v27, v2
	v_mov_b32_e32 v28, v2
	v_mov_b32_e32 v29, v2
	v_mov_b32_e32 v30, v2
	v_mov_b32_e32 v31, v2
	v_mov_b32_e32 v32, v2
	v_mov_b32_e32 v33, v2
	v_mov_b32_e32 v34, v2
	v_mov_b32_e32 v35, v2
	v_mov_b32_e32 v36, v2
	v_mov_b32_e32 v37, v2
	v_mov_b32_e32 v38, v2
	v_mov_b32_e32 v39, v2
	v_mov_b32_e32 v40, v2
	v_mov_b32_e32 v41, v2
	v_mov_b32_e32 v42, v2
	v_mov_b32_e32 v43, v2
	v_mov_b32_e32 v44, v2
	v_mov_b32_e32 v45, v2
	v_mov_b32_e32 v46, v2
	v_mov_b32_e32 v47, v2
	v_mov_b32_e32 v48, v2
	v_mov_b32_e32 v49, v2
	v_mov_b32_e32 v50, v2
	v_mov_b32_e32 v51, v2
	v_mov_b32_e32 v52, v2
	v_mov_b32_e32 v53, v2
	v_mov_b32_e32 v54, v2
	v_mov_b32_e32 v55, v2
	v_mov_b32_e32 v56, v2
	v_mov_b32_e32 v57, v2
	v_mov_b32_e32 v58, v2
	v_mov_b32_e32 v59, v2
	v_mov_b32_e32 v60, v2
	v_mov_b32_e32 v61, v2
	v_mov_b32_e32 v62, v2
	v_mov_b32_e32 v63, v2
	v_mov_b32_e32 v64, v2
	v_mov_b32_e32 v65, v2
	v_mov_b32_e32 v66, v2
	v_mov_b32_e32 v67, v2
	v_mov_b32_e32 v68, v2
	v_mov_b32_e32 v69, v2
	v_mov_b32_e32 v70, v2
	v_mov_b32_e32 v71, v2
	v_mov_b32_e32 v72, v2
	v_mov_b32_e32 v73, v2
	v_mov_b32_e32 v74, v2
	v_mov_b32_e32 v75, v2
	v_mov_b32_e32 v76, v2
	v_mov_b32_e32 v77, v2
	v_mov_b32_e32 v78, v2
	v_mov_b32_e32 v79, v2
	v_mov_b32_e32 v80, v2
	v_mov_b32_e32 v81, v2
	v_mov_b32_e32 v82, v2
	v_mov_b32_e32 v83, v2
	v_mov_b32_e32 v84, v2
	v_mov_b32_e32 v85, v2
	v_mov_b32_e32 v86, v2
	v_mov_b32_e32 v87, v2
	v_mov_b32_e32 v88, v2
	v_mov_b32_e32 v89, v2
	v_mov_b32_e32 v90, v2
	v_mov_b32_e32 v91, v2
	v_mov_b32_e32 v92, v2
	v_mov_b32_e32 v93, v2
	v_mov_b32_e32 v94, v2
	v_mov_b32_e32 v95, v2
	v_mov_b32_e32 v96, v2
	v_mov_b32_e32 v97, v2
	v_mov_b32_e32 v98, v2
	v_mov_b32_e32 v99, v2
	v_mov_b32_e32 v100, v2
	v_mov_b32_e32 v101, v2
	v_mov_b32_e32 v102, v2
	v_mov_b32_e32 v103, v2
	v_mov_b32_e32 v104, v2
	v_mov_b32_e32 v105, v2
	v_mov_b32_e32 v106, v2
	v_mov_b32_e32 v107, v2
	v_mov_b32_e32 v108, v2
	v_mov_b32_e32 v109, v2
	v_mov_b32_e32 v110, v2
	v_mov_b32_e32 v111, v2
	v_mov_b32_e32 v112, v2
	v_mov_b32_e32 v113, v2
	v_mov_b32_e32 v114, v2
	v_mov_b32_e32 v115, v2
	v_mov_b32_e32 v116, v2
	v_mov_b32_e32 v117, v2
	v_mov_b32_e32 v118, v2
	v_mov_b32_e32 v119, v2
	v_mov_b32_e32 v120, v2
	v_mov_b32_e32 v121, v2
	v_mov_b32_e32 v122, v2
	v_mov_b32_e32 v123, v2
	v_mov_b32_e32 v124, v2
	v_mov_b32_e32 v125, v2
	v_mov_b32_e32 v126, v2
	v_mov_b32_e32 v127, v2
	v_mov_b32_e32 v128, v2
	v_mov_b32_e32 v129, v2
	v_lshl_add_u64 v[142:143], s[30:31], 0, v[130:131]
	s_barrier

	.amdhsa_kernel _Z9hymba_fwd6Params
		.amdhsa_group_segment_fixed_size 0
		.amdhsa_private_segment_fixed_size 0
		.amdhsa_kernarg_size 520
		.amdhsa_user_sgpr_count 2
		.amdhsa_user_sgpr_dispatch_ptr 0
		.amdhsa_user_sgpr_queue_ptr 0
		.amdhsa_user_sgpr_kernarg_segment_ptr 1
		.amdhsa_user_sgpr_dispatch_id 0
		.amdhsa_user_sgpr_kernarg_preload_length 0
		.amdhsa_user_sgpr_kernarg_preload_offset 0
		.amdhsa_user_sgpr_private_segment_size 0
		.amdhsa_uses_dynamic_stack 0
		.amdhsa_enable_private_segment 0
		.amdhsa_system_sgpr_workgroup_id_x 1
		.amdhsa_system_sgpr_workgroup_id_y 0
		.amdhsa_system_sgpr_workgroup_id_z 0
		.amdhsa_system_sgpr_workgroup_info 0
		.amdhsa_system_vgpr_workitem_id 0
		.amdhsa_next_free_vgpr 256
		.amdhsa_next_free_sgpr 98
		.amdhsa_accum_offset 256
		.amdhsa_reserve_vcc 1
		.amdhsa_float_round_mode_32 0
		.amdhsa_float_round_mode_16_64 0
		.amdhsa_float_denorm_mode_32 3
		.amdhsa_float_denorm_mode_16_64 3
		.amdhsa_dx10_clamp 1
		.amdhsa_ieee_mode 1
		.amdhsa_fp16_overflow 0
		.amdhsa_tg_split 0
		.amdhsa_exception_fp_ieee_invalid_op 0
		.amdhsa_exception_fp_denorm_src 0
		.amdhsa_exception_fp_ieee_div_zero 0
		.amdhsa_exception_fp_ieee_overflow 0
		.amdhsa_exception_fp_ieee_underflow 0
		.amdhsa_exception_fp_ieee_inexact 0
		.amdhsa_exception_int_div_zero 0
	.end_amdhsa_kernel

.Lfunc_end0:
	.size	_Z9hymba_fwd6Params, .Lfunc_end0-_Z9hymba_fwd6Params
	.set _Z9hymba_fwd6Params.num_vgpr, 256
	.set _Z9hymba_fwd6Params.num_agpr, 0
	.set _Z9hymba_fwd6Params.numbered_sgpr, 98
	.set _Z9hymba_fwd6Params.num_named_barrier, 0
	.set _Z9hymba_fwd6Params.private_seg_size, 0
	.set _Z9hymba_fwd6Params.uses_vcc, 1
	.set _Z9hymba_fwd6Params.uses_flat_scratch, 0
	.set _Z9hymba_fwd6Params.has_dyn_sized_stack, 0
	.set _Z9hymba_fwd6Params.has_recursion, 0
	.set _Z9hymba_fwd6Params.has_indirect_call, 0

amdhsa.kernels:
  - .agpr_count:     0
    .args:
      - .offset:         0
        .size:           264
        .value_kind:     by_value
      - .offset:         264
        .size:           4
        .value_kind:     hidden_block_count_x
      - .offset:         268
        .size:           4
        .value_kind:     hidden_block_count_y
      - .offset:         272
        .size:           4
        .value_kind:     hidden_block_count_z
      - .offset:         276
        .size:           2
        .value_kind:     hidden_group_size_x
      - .offset:         278
        .size:           2
        .value_kind:     hidden_group_size_y
      - .offset:         280
        .size:           2
        .value_kind:     hidden_group_size_z
      - .offset:         282
        .size:           2
        .value_kind:     hidden_remainder_x
      - .offset:         284
        .size:           2
        .value_kind:     hidden_remainder_y
      - .offset:         286
        .size:           2
        .value_kind:     hidden_remainder_z
      - .offset:         304
        .size:           8
        .value_kind:     hidden_global_offset_x
      - .offset:         312
        .size:           8
        .value_kind:     hidden_global_offset_y
      - .offset:         320
        .size:           8
        .value_kind:     hidden_global_offset_z
      - .offset:         328
        .size:           2
        .value_kind:     hidden_grid_dims
      - .offset:         384
        .size:           4
        .value_kind:     hidden_dynamic_lds_size
    .group_segment_fixed_size: 0
    .kernarg_segment_align: 8
    .kernarg_segment_size: 520
    .language:       OpenCL C
    .language_version:
      - 2
      - 0
    .max_flat_workgroup_size: 512
    .name:           _Z9hymba_fwd6Params
    .private_segment_fixed_size: 0
    .sgpr_count:     104
    .sgpr_spill_count: 95
    .symbol:         _Z9hymba_fwd6Params.kd
    .uniform_work_group_size: 1
    .uses_dynamic_stack: false
    .vgpr_count:     256
    .vgpr_spill_count: 0
    .wavefront_size: 64
